# group start stagger with a quadratic offset distribution (idx^2/32 steps of s_sleep 5; same maximum, smaller mean)
# baseline (speedup 1.0000x reference)
; #define LAS __attribute__((address_space(3)))
; __device__ __forceinline__ bool attn_unit(const Ptrs& P, LAS unsigned char* lds, int unit, int tid, int wave, int lane, bool pre, int nxt) {
;     const int n = unit & 31, kh = (unit >> 5) & 3, b = unit >> 7;
;     const int g = wave & 3, q0 = 64 * (wave >> 2), h = kh * 4 + g, r = lane & 31, hh = lane >> 5;
;     unsigned char* ws = P.ws;
;     bf16_t* Qb = (bf16_t*)(ws + WS_Q) + (size_t)(b * SEQ + n * 128 + q0) * DM + h * 64;
;     const bf16_t* Kg = (const bf16_t*)(ws + WS_K) + (size_t)b * SEQ * KVW + kh * 64; const bf16_t* Vg = (const bf16_t*)(ws + WS_VT) + (size_t)(b * 4 + kh) * 64 * SEQ;
;     const bf16_t* Kcg = (const bf16_t*)(ws + WS_KC) + (size_t)b * CTX * KVW + kh * 64; const bf16_t* Vcg = (const bf16_t*)(ws + WS_VCT) + (size_t)(b * 4 + kh) * 64 * CTX;
;     float mq = fabsf(P.qg[lane]), mk = fabsf(P.kg[lane]);
; #pragma unroll
;     for (int o = 1; o < 64; o <<= 1) { mq = fmaxf(mq, __shfl_xor(mq, o)); mk = fmaxf(mk, __shfl_xor(mk, o)); }
;     const float sink2 = P.sink[h] * LOG2E; const float mshift = fmaxf(64.0f * QSCALE * mq * mk, sink2);
;     bf16x8_t qf[2][4];
; #pragma unroll
;     for (int cb = 0; cb < 2; ++cb)
; #pragma unroll
;         for (int ds = 0; ds < 4; ++ds) qf[cb][ds] = __builtin_nontemporal_load((const bf16x8_t*)(Qb + (size_t)(32 * cb + r) * DM + 16 * ds + 8 * hh));
;     f32x16 o[2][2];
; #pragma unroll
;     for (int db = 0; db < 2; ++db)
; #pragma unroll
;         for (int cb = 0; cb < 2; ++cb)
; #pragma unroll
;             for (int i = 0; i < 16; ++i) o[db][cb][i] = 0.f;
;     float rs[2] = {0.f, 0.f};
;     f32x16 negm;
; #pragma unroll
;     for (int i = 0; i < 16; ++i) negm[i] = -mshift;
; __device__ __forceinline__ void mk_p3(const Ptrs& P, LAS unsigned char* lds, int tid, int wave, int lane, int bx, int G, bool dry) {
;     ...
;         { bool pre = false; for (int u = bx; u < NB * 32 * 4; u += G) pre = attn_unit(P, lds, u, tid, wave, lane, pre, u + G < NB * 32 * 4 ? u + G : -1); }
.LBB9_305:
	s_cmp_lt_i32 s92, 4
	s_cselect_b64 s[2:3], -1, 0
	s_and_b64 s[22:23], s[2:3], s[0:1]
	s_andn2_b64 vcc, exec, s[22:23]
	s_cbranch_vccnz .LBB9_444
	v_writelane_b32 v251, s22, 33
	s_cmpk_gt_i32 s97, 0x1ff
	v_and_b32_e32 v171, 31, v208
	v_writelane_b32 v251, s23, 34
	v_writelane_b32 v251, s80, 35
	v_lshrrev_b32_e32 v184, 5, v170
	s_nop 0
	v_writelane_b32 v251, s81, 36
	v_writelane_b32 v251, s96, 37
	v_writelane_b32 v251, s83, 38
	v_writelane_b32 v251, s97, 39
	s_cbranch_scc1 .LBB9_413
	v_mbcnt_lo_u32_b32 v0, -1, 0
	v_mbcnt_hi_u32_b32 v0, -1, v0
	v_and_b32_e32 v1, 64, v0
	v_add_u32_e32 v1, 64, v1
	v_xor_b32_e32 v2, 1, v0
	v_cmp_lt_i32_e32 vcc, v2, v1
	s_bfe_u32 s0, s40, 0x20006
	v_writelane_b32 v251, s0, 40
	v_cndmask_b32_e32 v2, v0, v2, vcc
	v_lshlrev_b32_e32 v185, 2, v2
	v_xor_b32_e32 v2, 2, v0
	v_cmp_lt_i32_e32 vcc, v2, v1
	s_lshl_b32 s0, s50, 4
	s_and_b32 s33, s0, 0x3fffffc0
	v_cndmask_b32_e32 v2, v0, v2, vcc
	v_lshlrev_b32_e32 v186, 2, v2
	v_xor_b32_e32 v2, 4, v0
	v_cmp_lt_i32_e32 vcc, v2, v1
	s_cmpk_lt_u32 s40, 0x8c0
	s_cselect_b64 s[54:55], -1, 0
	v_cndmask_b32_e32 v2, v0, v2, vcc
	v_lshlrev_b32_e32 v187, 2, v2
	v_xor_b32_e32 v2, 8, v0
	v_cmp_lt_i32_e32 vcc, v2, v1
	s_or_b32 s2, s0, 63
	s_or_b32 s3, s33, 32
	v_cndmask_b32_e32 v2, v0, v2, vcc
	v_lshlrev_b32_e32 v188, 2, v2
	v_xor_b32_e32 v2, 16, v0
	v_cmp_lt_i32_e32 vcc, v2, v1
	v_or_b32_e32 v5, 32, v170
	v_lshlrev_b32_e32 v191, 4, v184
	v_cndmask_b32_e32 v2, v0, v2, vcc
	v_lshlrev_b32_e32 v189, 2, v2
	v_xor_b32_e32 v2, 32, v0
	v_cmp_lt_i32_e32 vcc, v2, v1
	v_mov_b32_e32 v1, 0
	v_mul_u32_u24_e32 v6, 0x110, v5
	v_cndmask_b32_e32 v0, v0, v2, vcc
	v_lshlrev_b32_e32 v190, 2, v0
	v_lshlrev_b32_e32 v0, 2, v184
	v_sub_u32_e32 v0, v171, v0
	v_cmp_lt_i32_e64 s[36:37], 10, v0
	v_cmp_gt_i32_e64 s[0:1], 1, v0
	v_cmp_gt_i32_e64 s[4:5], 2, v0
	v_writelane_b32 v251, s36, 41
	v_cmp_gt_i32_e64 s[6:7], 3, v0
	v_cmp_gt_i32_e64 s[8:9], 4, v0
	v_writelane_b32 v251, s37, 42
	v_cmp_lt_i32_e64 s[36:37], 15, v0
	v_cmp_gt_i32_e64 s[10:11], 9, v0
	v_cmp_gt_i32_e64 s[12:13], 10, v0
	v_writelane_b32 v251, s36, 43
	v_cmp_gt_i32_e64 s[14:15], 11, v0
	v_cmp_gt_i32_e64 s[16:17], 12, v0
	v_writelane_b32 v251, s37, 44
	v_cmp_lt_i32_e64 s[36:37], 16, v0
	v_cmp_gt_i32_e64 s[18:19], 17, v0
	v_cmp_gt_i32_e64 s[20:21], 18, v0
	v_writelane_b32 v251, s36, 45
	v_cmp_gt_i32_e64 s[22:23], 19, v0
	v_cmp_gt_i32_e64 s[24:25], 20, v0
	v_writelane_b32 v251, s37, 46
	v_cmp_lt_i32_e64 s[36:37], 17, v0
	v_cmp_gt_i32_e64 s[26:27], 25, v0
	v_cmp_gt_i32_e64 s[28:29], 26, v0
	v_writelane_b32 v251, s36, 47
	v_cmp_gt_i32_e64 s[30:31], 27, v0
	v_cmp_gt_i32_e64 s[34:35], 28, v0
	v_writelane_b32 v251, s37, 48
	v_cmp_lt_i32_e64 s[36:37], 18, v0
	v_cmp_lt_i32_e64 s[56:57], -1, v0
	v_cmp_lt_i32_e64 s[86:87], 0, v0
	v_writelane_b32 v251, s36, 49
	v_cmp_lt_i32_e64 s[60:61], 1, v0
	v_cmp_lt_i32_e64 s[62:63], 2, v0
	v_writelane_b32 v251, s37, 50
	v_cmp_lt_i32_e64 s[36:37], 23, v0
	v_cmp_lt_i32_e64 s[64:65], 7, v0
	v_cmp_lt_i32_e64 s[66:67], 8, v0
	v_writelane_b32 v251, s36, 51
	v_cmp_lt_i32_e64 s[72:73], 9, v0
	v_lshlrev_b32_e32 v4, 3, v184
	v_writelane_b32 v251, s37, 52
	v_cmp_lt_i32_e64 s[36:37], 24, v0
	v_mul_u32_u24_e32 v3, 0x110, v171
	v_lshlrev_b32_e32 v2, 10, v171
	v_writelane_b32 v251, s36, 53
	s_movk_i32 s52, 0x110
	v_add3_u32 v3, v3, v191, 0
	v_writelane_b32 v251, s37, 54
	v_cmp_lt_i32_e64 s[36:37], 25, v0
	v_lshlrev_b32_e32 v176, 1, v4
	s_mov_b32 s77, 0
	v_writelane_b32 v251, s36, 55
	v_add_u32_e32 v195, 0x4800, v3
	v_add_u32_e32 v198, 0xd400, v3
	v_writelane_b32 v251, s37, 56
	v_cmp_lt_i32_e64 s[36:37], 26, v0
	v_lshlrev_b32_e32 v0, 2, v170
	v_mad_u32_u24 v200, v5, s52, 0
	v_writelane_b32 v251, s36, 57
	v_mad_u32_u24 v201, v171, s52, 0
	s_mov_b64 s[68:69], 0
	v_writelane_b32 v251, s37, 58
	s_add_u32 s36, s90, 0x6200000
	v_writelane_b32 v251, s36, 59
	s_addc_u32 s36, s91, 0
	v_writelane_b32 v251, s36, 60
	s_add_u32 s36, s90, 0x7200000
	v_writelane_b32 v251, s36, 61
	s_addc_u32 s36, s91, 0
	v_writelane_b32 v251, s36, 62
	v_mov_b32_e32 v178, v176
	v_readlane_b32 s36, v251, 16
	s_add_u32 s36, s90, 0x4200000
	v_readlane_b32 s37, v251, 17
	v_readlane_b32 s38, v251, 18
	v_readlane_b32 s39, v251, 19
	v_readlane_b32 s40, v251, 20
	v_readlane_b32 s41, v251, 21
	v_readlane_b32 s42, v251, 22
	v_readlane_b32 s43, v251, 23
	v_readlane_b32 s44, v251, 24
	v_readlane_b32 s45, v251, 25
	v_readlane_b32 s46, v251, 26
	v_readlane_b32 s47, v251, 27
	v_readlane_b32 s48, v251, 28
	v_readlane_b32 s49, v251, 29
	v_readlane_b32 s50, v251, 30
	v_readlane_b32 s51, v251, 31
	v_writelane_b32 v251, s36, 63
	s_addc_u32 s36, s91, 0
	v_writelane_b32 v250, s36, 0
	s_add_u32 s36, s90, 0x6a00000
	v_writelane_b32 v250, s36, 1
	s_addc_u32 s36, s91, 0
	v_writelane_b32 v250, s36, 2
	s_add_u32 s36, s90, 0x7280000
	v_writelane_b32 v250, s36, 3
	s_addc_u32 s36, s91, 0
	v_writelane_b32 v250, s36, 4
	s_add_u32 s36, s90, 0x2000000
	v_writelane_b32 v250, s36, 5
	s_addc_u32 s36, s91, 0
	v_lshl_add_u64 v[172:173], s[40:41], 0, v[0:1]
	v_writelane_b32 v250, s36, 6
	s_add_i32 s40, 0, 0x11800
	s_add_i32 s76, 0, 0x16000
	v_writelane_b32 v250, s40, 7
	v_writelane_b32 v250, s76, 8
	v_writelane_b32 v250, s88, 9
	v_lshl_add_u64 v[174:175], s[42:43], 0, v[0:1]
	v_readlane_b32 s36, v251, 32
	v_writelane_b32 v250, s89, 10
	v_writelane_b32 v250, s90, 11
	v_writelane_b32 v250, s91, 12
	v_add3_u32 v0, v6, v191, 0
	v_mul_u32_u24_e32 v6, 0x90, v171
	v_writelane_b32 v250, s92, 13
	v_lshl_or_b32 v192, s36, 6, v170
	s_movk_i32 s37, 0x90
	v_add3_u32 v196, v6, v191, 0
	v_writelane_b32 v250, s93, 14
	v_add_u32_e32 v193, 0xfffffb80, v192
	v_add_u32_e32 v194, 0x4800, v0
	v_add_u32_e32 v197, 0xd400, v0
	v_add_u32_e32 v199, 0x8c00, v196
	v_mad_u32_u24 v202, v171, s37, 0
	v_mov_b32_e32 v179, v1
	v_lshlrev_b32_e32 v180, 1, v2
	v_mov_b32_e32 v181, v1
	s_mov_b32 s36, 0xf0f0f0f1
	s_movk_i32 s37, 0xffef
	s_movk_i32 s38, 0x490
	s_mov_b32 s39, 0x38e38e39
	v_readlane_b32 s42, v251, 39
	v_writelane_b32 v250, s94, 22
	v_writelane_b32 v250, s94, 23
	v_mov_b32_e32 v254, 0x24008
	ds_read_b32 v254, v254
	s_waitcnt lgkmcnt(0)
	v_readfirstlane_b32 s98, v254
	s_nop 3
	s_cmp_eq_u32 s98, 1
	s_cbranch_scc0 .Lrm_a
	s_cmpk_lg_i32 s94, 0x100
	s_cbranch_scc1 .Lrm_a
	s_and_b32 s98, s42, 7
	s_lshl_b32 s98, s98, 3
	s_bfe_u32 s99, s42, 0x30003
	s_or_b32 s98, s98, s99
	s_and_b32 vcc_lo, s98, 7
	s_lshl_b32 vcc_lo, vcc_lo, 3
	s_lshr_b32 vcc_hi, s98, 3
	s_or_b32 vcc_lo, vcc_lo, vcc_hi
	s_nop 0
	s_mul_i32 vcc_lo, vcc_lo, vcc_lo
	s_lshr_b32 vcc_lo, vcc_lo, 5
.Lstg_loop:
	s_cmp_eq_u32 vcc_lo, 0
	s_cbranch_scc1 .Lstg_done
	s_sleep 5
	s_sub_u32 vcc_lo, vcc_lo, 1
	s_branch .Lstg_loop
